# E phases with bf16 residual: deferred bf16 unpack of the prefetched row (no vmcnt drain behind the prefetch loads); plus attention: max folded into MFMA C, V-fragment reads interleaved with PV MFMAs
# baseline (speedup 1.0000x reference)
; #define GAS __attribute__((address_space(1)))
; DI unsigned pk2(float lo, float hi) { f32x2_t v = {lo, hi}; bf16x2_t b = __builtin_convertvector(v, bf16x2_t); return __builtin_bit_cast(unsigned, b); }
; DI void phase_e(const Ctx& C, int nslab, int has_post, int pl, int ps, float pw, int has_pre, int ql, int qs, int nrows,
;                 const GAS float* xsrc, const GAS float* csrc, GAS float* xdst, GAS float* cdst, bool xs16, bool xd16) {
;     ...
;         if (has_pre) {
;             float ss = 0.f;
; #pragma unroll
;             for (int j = 0; j < 4; ++j) ss += (v[j][0] * v[j][0] + v[j][1] * v[j][1]) + (v[j][2] * v[j][2] + v[j][3] * v[j][3]);
;             const float r = rsqrtf(wave_sum(ss) * (1.0f / 1024.0f) + EPS);
; #pragma unroll
;             for (int j = 0; j < 4; ++j) { const f32x4 h = ((v[j] * r) * gpr[j]) * (1.0f + sc[j]) + sh[j];
;                 u32x2 w; w.x = pk2(h[0], h[1]); w.y = pk2(h[2], h[3]); *(GAS u32x2*)(H + (size_t)row * 1024 + 256 * j + 4 * lane) = w; }
;         }
.LBB0_945:
	v_pk_mul_f32 v[54:55], v[80:81], v[80:81]
	v_pk_mul_f32 v[56:57], v[78:79], v[78:79]
	v_pk_mul_f32 v[46:47], v[132:133], v[132:133]
	v_pk_mul_f32 v[48:49], v[130:131], v[130:131]
	v_pk_mov_b32 v[58:59], v[56:57], v[54:55] op_sel:[1,0]
	v_mov_b32_e32 v57, v55
	v_pk_add_f32 v[54:55], v[58:59], v[56:57]
	v_pk_mov_b32 v[56:57], v[48:49], v[46:47] op_sel:[1,0]
	v_mov_b32_e32 v49, v47
	v_pk_add_f32 v[46:47], v[56:57], v[48:49]
	v_pk_add_f32 v[54:55], v[54:55], v[54:55] op_sel_hi:[0,1]
	v_pk_add_f32 v[46:47], v[46:47], v[46:47] op_sel_hi:[0,1]
	v_mul_f32_e32 v46, v134, v134
	v_pk_fma_f32 v[48:49], v[134:135], v[134:135], v[46:47] op_sel_hi:[1,1,0]
	v_mul_f32_e32 v46, v136, v136
	v_pk_fma_f32 v[56:57], v[136:137], v[136:137], v[46:47] op_sel_hi:[1,1,0]
	v_mul_f32_e32 v48, v138, v138
	v_mul_f32_e32 v56, v139, v139
	v_mul_f32_e32 v54, v140, v140
	v_mul_f32_e32 v46, v141, v141
	v_pk_add_f32 v[48:49], v[48:49], v[56:57]
	v_pk_add_f32 v[46:47], v[54:55], v[46:47]
	s_waitcnt vmcnt(10)
	v_pk_add_f32 v[54:55], v[66:67], 1.0 op_sel_hi:[1,0]
	v_pk_add_f32 v[46:47], v[48:49], v[46:47]
	v_pk_add_f32 v[48:49], v[68:69], 1.0 op_sel_hi:[1,0]
	v_add_f32_e32 v46, v46, v47
	ds_bpermute_b32 v47, v186, v46
	s_add_i32 s0, s23, 8
	s_add_i32 s1, s23, -8
	s_cmp_lt_i32 s1, s17
	s_mov_b32 s23, s0
	s_waitcnt lgkmcnt(0)
	v_add_f32_e32 v46, v46, v47
	ds_bpermute_b32 v47, v187, v46
	s_waitcnt lgkmcnt(0)
	v_add_f32_e32 v46, v46, v47
	ds_bpermute_b32 v47, v188, v46
	s_waitcnt lgkmcnt(0)
	v_add_f32_e32 v46, v46, v47
	ds_bpermute_b32 v47, v189, v46
	s_waitcnt lgkmcnt(0)
	v_add_f32_e32 v46, v46, v47
	ds_bpermute_b32 v47, v190, v46
	s_waitcnt lgkmcnt(0)
	v_add_f32_e32 v46, v46, v47
	ds_bpermute_b32 v47, v191, v46
	s_waitcnt lgkmcnt(0)
	v_add_f32_e32 v46, v46, v47
	v_fmamk_f32 v46, v46, 0x3a800000, v192
	v_mul_f32_e32 v47, 0x4b800000, v46
	v_cmp_gt_f32_e32 vcc, s27, v46
	s_nop 1
	v_cndmask_b32_e32 v46, v46, v47, vcc
	v_rsq_f32_e32 v56, v46
	v_lshl_add_u64 v[46:47], v[158:159], 0, s[2:3]
	v_mul_f32_e32 v57, 0x45800000, v56
	v_cndmask_b32_e32 v56, v56, v57, vcc
	v_pk_mul_f32 v[58:59], v[80:81], v[56:57] op_sel_hi:[1,0]
	v_pk_mul_f32 v[60:61], v[78:79], v[56:57] op_sel_hi:[1,0]
	v_pk_mul_f32 v[58:59], v[12:13], v[58:59]
	v_pk_mul_f32 v[60:61], v[10:11], v[60:61]
	s_waitcnt vmcnt(9)
	v_pk_fma_f32 v[48:49], v[48:49], v[58:59], v[72:73]
	v_pk_fma_f32 v[54:55], v[54:55], v[60:61], v[70:71]
	v_pk_mul_f32 v[78:79], v[132:133], v[56:57] op_sel_hi:[1,0]
	v_pk_mul_f32 v[80:81], v[130:131], v[56:57] op_sel_hi:[1,0]
	v_cvt_pk_bf16_f32 v54, v54, v55
	v_cvt_pk_bf16_f32 v55, v48, v49
	v_pk_mul_f32 v[80:81], v[14:15], v[80:81]
	global_store_dwordx2 v[46:47], v[54:55], off
	v_pk_mul_f32 v[48:49], v[16:17], v[78:79]
	s_waitcnt vmcnt(6)
	v_pk_add_f32 v[54:55], v[76:77], 1.0 op_sel_hi:[1,0]
	v_pk_add_f32 v[58:59], v[74:75], 1.0 op_sel_hi:[1,0]
	v_pk_fma_f32 v[48:49], v[54:55], v[48:49], v[84:85]
	v_pk_fma_f32 v[54:55], v[58:59], v[80:81], v[82:83]
	s_waitcnt vmcnt(4)
	v_pk_add_f32 v[58:59], v[88:89], 1.0 op_sel_hi:[1,0]
	v_cvt_pk_bf16_f32 v54, v54, v55
	v_cvt_pk_bf16_f32 v55, v48, v49
	global_store_dwordx2 v[46:47], v[54:55], off offset:512
	v_pk_mul_f32 v[48:49], v[136:137], v[56:57] op_sel_hi:[1,0]
	v_pk_mul_f32 v[54:55], v[134:135], v[56:57] op_sel_hi:[1,0]
	v_pk_mul_f32 v[48:49], v[28:29], v[48:49]
	v_pk_mul_f32 v[54:55], v[26:27], v[54:55]
	v_pk_add_f32 v[60:61], v[86:87], 1.0 op_sel_hi:[1,0]
	s_waitcnt vmcnt(3)
	v_pk_fma_f32 v[48:49], v[58:59], v[48:49], v[96:97]
	v_pk_fma_f32 v[54:55], v[60:61], v[54:55], v[94:95]
	v_pk_add_f32 v[58:59], v[62:63], 1.0 op_sel_hi:[1,0]
	v_cvt_pk_bf16_f32 v54, v54, v55
	v_cvt_pk_bf16_f32 v55, v48, v49
	global_store_dwordx2 v[46:47], v[54:55], off offset:1024
	v_pk_mul_f32 v[48:49], v[140:141], v[56:57] op_sel_hi:[1,0]
	v_pk_mul_f32 v[54:55], v[138:139], v[56:57] op_sel_hi:[1,0]
	v_pk_mul_f32 v[48:49], v[32:33], v[48:49]
	v_pk_mul_f32 v[54:55], v[30:31], v[54:55]
	v_pk_add_f32 v[56:57], v[64:65], 1.0 op_sel_hi:[1,0]
	s_waitcnt vmcnt(3)
	v_pk_fma_f32 v[54:55], v[58:59], v[54:55], v[90:91]
	v_pk_fma_f32 v[48:49], v[56:57], v[48:49], v[92:93]
	v_cvt_pk_bf16_f32 v54, v54, v55
	v_cvt_pk_bf16_f32 v55, v48, v49
	global_store_dwordx2 v[46:47], v[54:55], off offset:1536
	s_mov_b64 vcc, s[98:99]
	s_cbranch_vccz .Leload_skip_0
	s_waitcnt vmcnt(8)
	v_lshlrev_b32_e32 v114, 16, v116
	v_and_b32_e32 v115, 0xffff0000, v116
	v_lshlrev_b32_e32 v116, 16, v117
	v_and_b32_e32 v117, 0xffff0000, v117
	v_lshlrev_b32_e32 v118, 16, v120
	v_and_b32_e32 v119, 0xffff0000, v120
	v_lshlrev_b32_e32 v120, 16, v121
	v_and_b32_e32 v121, 0xffff0000, v121
	v_lshlrev_b32_e32 v122, 16, v124
	v_and_b32_e32 v123, 0xffff0000, v124
	v_lshlrev_b32_e32 v124, 16, v125
	v_and_b32_e32 v125, 0xffff0000, v125
	v_lshlrev_b32_e32 v126, 16, v128
	v_and_b32_e32 v127, 0xffff0000, v128
	v_lshlrev_b32_e32 v128, 16, v129
	v_and_b32_e32 v129, 0xffff0000, v129
.Leload_skip_0:
	v_mov_b64_e32 v[46:47], v[50:51]
	v_mov_b64_e32 v[56:57], v[44:45]
	v_mov_b64_e32 v[60:61], v[40:41]
	v_mov_b64_e32 v[80:81], v[36:37]
	v_mov_b64_e32 v[48:49], v[52:53]
	v_mov_b64_e32 v[54:55], v[42:43]
	v_mov_b64_e32 v[58:59], v[38:39]
	v_mov_b64_e32 v[78:79], v[34:35]
	v_mov_b64_e32 v[50:51], v[126:127]
	v_mov_b64_e32 v[42:43], v[122:123]
	v_mov_b64_e32 v[38:39], v[118:119]
	v_mov_b64_e32 v[34:35], v[114:115]
	v_mov_b64_e32 v[52:53], v[128:129]
	v_mov_b64_e32 v[44:45], v[124:125]
	v_mov_b64_e32 v[40:41], v[120:121]
	v_mov_b64_e32 v[36:37], v[116:117]
	v_mov_b64_e32 v[130:131], v[150:151]
	v_mov_b64_e32 v[132:133], v[148:149]
	v_mov_b64_e32 v[134:135], v[146:147]
	v_mov_b64_e32 v[136:137], v[144:145]
	v_mov_b64_e32 v[150:151], v[168:169]
	v_mov_b64_e32 v[148:149], v[166:167]
	v_mov_b64_e32 v[146:147], v[164:165]
	v_mov_b64_e32 v[144:145], v[162:163]
	s_cbranch_scc0 .LBB0_975
.LBB0_946:
	s_mov_b64 s[98:99], 0
	s_cmp_ge_i32 s23, s17
	s_cbranch_scc1 .LBB0_953
	s_add_i32 s1, s22, s23
	s_add_i32 s0, s21, s23
	s_add_i32 s1, s1, 0x8000
	s_cmp_lt_i32 s23, s16
	s_cselect_b32 s0, s0, s1
	s_cmp_lt_i32 s0, 0x8000
	s_cselect_b64 s[2:3], -1, 0
	s_cmpk_gt_i32 s0, 0x7fff
	s_mov_b64 s[10:11], -1
	s_cbranch_scc0 .LBB0_949
	s_add_i32 s4, s0, 0xffff8000
	s_lshl_b64 s[10:11], s[4:5], 12
	v_lshl_add_u64 v[126:127], v[160:161], 0, s[10:11]
	global_load_dwordx4 v[114:117], v[126:127], off nt
	global_load_dwordx4 v[118:121], v[126:127], off offset:1024 nt
	global_load_dwordx4 v[122:125], v[126:127], off offset:2048 nt
	s_nop 0
	global_load_dwordx4 v[126:129], v[126:127], off offset:3072 nt
	s_mov_b64 s[10:11], 0
.LBB0_949:
	s_andn2_b64 vcc, exec, s[10:11]
	s_cbranch_vccnz .LBB0_951
	s_ashr_i32 s1, s0, 31
	s_lshl_b64 s[10:11], s[0:1], 11
	s_waitcnt vmcnt(3)
	v_lshl_add_u64 v[114:115], v[152:153], 0, s[10:11]
	global_load_dwordx2 v[116:117], v[114:115], off nt
	global_load_dwordx2 v[120:121], v[114:115], off offset:512 nt
	global_load_dwordx2 v[124:125], v[114:115], off offset:1024 nt
	global_load_dwordx2 v[128:129], v[114:115], off offset:1536 nt
	s_mov_b64 s[98:99], -1

; #define GAS __attribute__((address_space(1)))
; DI unsigned pk2(float lo, float hi) { f32x2_t v = {lo, hi}; bf16x2_t b = __builtin_convertvector(v, bf16x2_t); return __builtin_bit_cast(unsigned, b); }
; DI void phase_e(const Ctx& C, int nslab, int has_post, int pl, int ps, float pw, int has_pre, int ql, int qs, int nrows,
;                 const GAS float* xsrc, const GAS float* csrc, GAS float* xdst, GAS float* cdst, bool xs16, bool xd16) {
;     ...
;         if (has_pre) {
;             float ss = 0.f;
; #pragma unroll
;             for (int j = 0; j < 4; ++j) ss += (v[j][0] * v[j][0] + v[j][1] * v[j][1]) + (v[j][2] * v[j][2] + v[j][3] * v[j][3]);
;             const float r = rsqrtf(wave_sum(ss) * (1.0f / 1024.0f) + EPS);
; #pragma unroll
;             for (int j = 0; j < 4; ++j) { const f32x4 h = ((v[j] * r) * gpr[j]) * (1.0f + sc[j]) + sh[j];
;                 u32x2 w; w.x = pk2(h[0], h[1]); w.y = pk2(h[2], h[3]); *(GAS u32x2*)(H + (size_t)row * 1024 + 256 * j + 4 * lane) = w; }
;         }
.LBB0_1212:
	v_pk_mul_f32 v[54:55], v[100:101], v[100:101]
	v_pk_mul_f32 v[56:57], v[98:99], v[98:99]
	v_pk_mul_f32 v[46:47], v[132:133], v[132:133]
	v_pk_mul_f32 v[48:49], v[130:131], v[130:131]
	v_pk_mov_b32 v[58:59], v[56:57], v[54:55] op_sel:[1,0]
	v_mov_b32_e32 v57, v55
	v_pk_add_f32 v[54:55], v[58:59], v[56:57]
	v_pk_mov_b32 v[56:57], v[48:49], v[46:47] op_sel:[1,0]
	v_mov_b32_e32 v49, v47
	v_pk_add_f32 v[46:47], v[56:57], v[48:49]
	v_pk_add_f32 v[54:55], v[54:55], v[54:55] op_sel_hi:[0,1]
	v_pk_add_f32 v[46:47], v[46:47], v[46:47] op_sel_hi:[0,1]
	v_mul_f32_e32 v46, v134, v134
	v_pk_fma_f32 v[48:49], v[134:135], v[134:135], v[46:47] op_sel_hi:[1,1,0]
	v_mul_f32_e32 v46, v136, v136
	v_pk_fma_f32 v[56:57], v[136:137], v[136:137], v[46:47] op_sel_hi:[1,1,0]
	v_mul_f32_e32 v48, v138, v138
	v_mul_f32_e32 v56, v139, v139
	v_mul_f32_e32 v54, v140, v140
	v_mul_f32_e32 v46, v141, v141
	v_pk_add_f32 v[48:49], v[48:49], v[56:57]
	v_pk_add_f32 v[46:47], v[54:55], v[46:47]
	v_pk_add_f32 v[54:55], v[66:67], 1.0 op_sel_hi:[1,0]
	v_pk_add_f32 v[46:47], v[48:49], v[46:47]
	v_pk_add_f32 v[48:49], v[68:69], 1.0 op_sel_hi:[1,0]
	v_add_f32_e32 v46, v46, v47
	ds_bpermute_b32 v47, v190, v46
	s_add_i32 s0, s22, 8
	s_add_i32 s1, s22, -8
	s_cmp_lt_i32 s1, s17
	s_mov_b32 s22, s0
	s_waitcnt lgkmcnt(0)
	v_add_f32_e32 v46, v46, v47
	ds_bpermute_b32 v47, v191, v46
	v_mov_b64_e32 v[170:171], v[144:145]
	s_waitcnt vmcnt(3)
	v_mov_b64_e32 v[144:145], v[162:163]
	s_waitcnt lgkmcnt(0)
	v_add_f32_e32 v46, v46, v47
	ds_bpermute_b32 v47, v192, v46
	s_waitcnt lgkmcnt(0)
	v_add_f32_e32 v46, v46, v47
	ds_bpermute_b32 v47, v193, v46
	s_waitcnt lgkmcnt(0)
	v_add_f32_e32 v46, v46, v47
	ds_bpermute_b32 v47, v194, v46
	s_waitcnt lgkmcnt(0)
	v_add_f32_e32 v46, v46, v47
	ds_bpermute_b32 v47, v195, v46
	s_waitcnt lgkmcnt(0)
	v_add_f32_e32 v46, v46, v47
	v_fmamk_f32 v46, v46, 0x3a800000, v196
	v_mul_f32_e32 v47, 0x4b800000, v46
	v_cmp_gt_f32_e32 vcc, s25, v46
	s_nop 1
	v_cndmask_b32_e32 v46, v46, v47, vcc
	v_rsq_f32_e32 v56, v46
	v_lshl_add_u64 v[46:47], v[158:159], 0, s[2:3]
	v_mul_f32_e32 v57, 0x45800000, v56
	v_cndmask_b32_e32 v56, v56, v57, vcc
	v_pk_mul_f32 v[58:59], v[100:101], v[56:57] op_sel_hi:[1,0]
	v_pk_mul_f32 v[60:61], v[98:99], v[56:57] op_sel_hi:[1,0]
	v_pk_mul_f32 v[58:59], v[12:13], v[58:59]
	v_pk_mul_f32 v[60:61], v[10:11], v[60:61]
	v_pk_fma_f32 v[48:49], v[48:49], v[58:59], v[72:73]
	v_pk_fma_f32 v[54:55], v[54:55], v[60:61], v[70:71]
	v_pk_mul_f32 v[98:99], v[132:133], v[56:57] op_sel_hi:[1,0]
	v_pk_mul_f32 v[100:101], v[130:131], v[56:57] op_sel_hi:[1,0]
	v_cvt_pk_bf16_f32 v54, v54, v55
	v_cvt_pk_bf16_f32 v55, v48, v49
	v_pk_mul_f32 v[100:101], v[14:15], v[100:101]
	global_store_dwordx2 v[46:47], v[54:55], off
	v_pk_mul_f32 v[48:49], v[16:17], v[98:99]
	v_pk_add_f32 v[54:55], v[76:77], 1.0 op_sel_hi:[1,0]
	v_pk_add_f32 v[58:59], v[74:75], 1.0 op_sel_hi:[1,0]
	v_pk_fma_f32 v[48:49], v[54:55], v[48:49], v[80:81]
	v_pk_fma_f32 v[54:55], v[58:59], v[100:101], v[78:79]
	v_pk_add_f32 v[58:59], v[84:85], 1.0 op_sel_hi:[1,0]
	v_cvt_pk_bf16_f32 v54, v54, v55
	v_cvt_pk_bf16_f32 v55, v48, v49
	global_store_dwordx2 v[46:47], v[54:55], off offset:512
	v_pk_mul_f32 v[48:49], v[136:137], v[56:57] op_sel_hi:[1,0]
	v_pk_mul_f32 v[54:55], v[134:135], v[56:57] op_sel_hi:[1,0]
	v_pk_mul_f32 v[48:49], v[28:29], v[48:49]
	v_pk_mul_f32 v[54:55], v[26:27], v[54:55]
	v_pk_add_f32 v[60:61], v[82:83], 1.0 op_sel_hi:[1,0]
	s_waitcnt vmcnt(3)
	v_pk_fma_f32 v[48:49], v[58:59], v[48:49], v[92:93]
	v_pk_fma_f32 v[54:55], v[60:61], v[54:55], v[90:91]
	v_pk_add_f32 v[58:59], v[62:63], 1.0 op_sel_hi:[1,0]
	v_cvt_pk_bf16_f32 v54, v54, v55
	v_cvt_pk_bf16_f32 v55, v48, v49
	global_store_dwordx2 v[46:47], v[54:55], off offset:1024
	v_pk_mul_f32 v[48:49], v[140:141], v[56:57] op_sel_hi:[1,0]
	v_pk_mul_f32 v[54:55], v[138:139], v[56:57] op_sel_hi:[1,0]
	v_pk_mul_f32 v[48:49], v[32:33], v[48:49]
	v_pk_mul_f32 v[54:55], v[30:31], v[54:55]
	v_pk_add_f32 v[56:57], v[64:65], 1.0 op_sel_hi:[1,0]
	s_waitcnt vmcnt(3)
	v_pk_fma_f32 v[54:55], v[58:59], v[54:55], v[86:87]
	v_pk_fma_f32 v[48:49], v[56:57], v[48:49], v[88:89]
	v_cvt_pk_bf16_f32 v54, v54, v55
	v_cvt_pk_bf16_f32 v55, v48, v49
	global_store_dwordx2 v[46:47], v[54:55], off offset:1536
	s_mov_b64 vcc, s[98:99]
	s_cbranch_vccz .Leload_skip_1
	s_waitcnt vmcnt(8)
	v_lshlrev_b32_e32 v114, 16, v116
	v_and_b32_e32 v115, 0xffff0000, v116
	v_lshlrev_b32_e32 v116, 16, v117
	v_and_b32_e32 v117, 0xffff0000, v117
	v_lshlrev_b32_e32 v118, 16, v120
	v_and_b32_e32 v119, 0xffff0000, v120
	v_lshlrev_b32_e32 v120, 16, v121
	v_and_b32_e32 v121, 0xffff0000, v121
	v_lshlrev_b32_e32 v122, 16, v124
	v_and_b32_e32 v123, 0xffff0000, v124
	v_lshlrev_b32_e32 v124, 16, v125
	v_and_b32_e32 v125, 0xffff0000, v125
	v_lshlrev_b32_e32 v126, 16, v128
	v_and_b32_e32 v127, 0xffff0000, v128
	v_lshlrev_b32_e32 v128, 16, v129
	v_and_b32_e32 v129, 0xffff0000, v129
.Leload_skip_1:
	v_mov_b64_e32 v[46:47], v[50:51]
	v_mov_b64_e32 v[56:57], v[44:45]
	v_mov_b64_e32 v[60:61], v[40:41]
	v_mov_b64_e32 v[100:101], v[36:37]
	v_mov_b64_e32 v[48:49], v[52:53]
	v_mov_b64_e32 v[54:55], v[42:43]
	v_mov_b64_e32 v[58:59], v[38:39]
	v_mov_b64_e32 v[98:99], v[34:35]
	v_mov_b64_e32 v[50:51], v[126:127]
	v_mov_b64_e32 v[42:43], v[122:123]
	v_mov_b64_e32 v[38:39], v[118:119]
	v_mov_b64_e32 v[34:35], v[114:115]
	v_mov_b64_e32 v[52:53], v[128:129]
	v_mov_b64_e32 v[44:45], v[124:125]
	v_mov_b64_e32 v[40:41], v[120:121]
	v_mov_b64_e32 v[36:37], v[116:117]
	v_mov_b64_e32 v[130:131], v[150:151]
	v_mov_b64_e32 v[132:133], v[148:149]
	v_mov_b64_e32 v[134:135], v[146:147]
	v_mov_b64_e32 v[150:151], v[168:169]
	v_mov_b64_e32 v[148:149], v[166:167]
	v_mov_b64_e32 v[146:147], v[164:165]
	s_cbranch_scc0 .LBB0_1242
.LBB0_1213:
	s_mov_b64 s[98:99], 0
	s_cmp_ge_i32 s22, s17
	s_cbranch_scc1 .LBB0_1220
	s_add_i32 s1, s21, s22
	s_add_i32 s0, s20, s22
	s_add_i32 s1, s1, 0x8000
	s_cmp_lt_i32 s22, s16
	s_cselect_b32 s0, s0, s1
	s_cmp_lt_i32 s0, 0x8000
	s_cselect_b64 s[2:3], -1, 0
	s_cmpk_gt_i32 s0, 0x7fff
	s_mov_b64 s[10:11], -1
	s_cbranch_scc0 .LBB0_1216
	s_add_i32 s4, s0, 0xffff8000
	s_lshl_b64 s[10:11], s[4:5], 12
	v_lshl_add_u64 v[126:127], v[160:161], 0, s[10:11]
	global_load_dwordx4 v[114:117], v[126:127], off nt
	global_load_dwordx4 v[118:121], v[126:127], off offset:1024 nt
	global_load_dwordx4 v[122:125], v[126:127], off offset:2048 nt
	s_nop 0
	global_load_dwordx4 v[126:129], v[126:127], off offset:3072 nt
	s_mov_b64 s[10:11], 0

; #define GAS __attribute__((address_space(1)))
; DI unsigned pk2(float lo, float hi) { f32x2_t v = {lo, hi}; bf16x2_t b = __builtin_convertvector(v, bf16x2_t); return __builtin_bit_cast(unsigned, b); }
; DI void phase_e(const Ctx& C, int nslab, int has_post, int pl, int ps, float pw, int has_pre, int ql, int qs, int nrows,
;                 const GAS float* xsrc, const GAS float* csrc, GAS float* xdst, GAS float* cdst, bool xs16, bool xd16) {
;     ...
;         if (has_pre) {
;             float ss = 0.f;
; #pragma unroll
;             for (int j = 0; j < 4; ++j) ss += (v[j][0] * v[j][0] + v[j][1] * v[j][1]) + (v[j][2] * v[j][2] + v[j][3] * v[j][3]);
;             const float r = rsqrtf(wave_sum(ss) * (1.0f / 1024.0f) + EPS);
; #pragma unroll
;             for (int j = 0; j < 4; ++j) { const f32x4 h = ((v[j] * r) * gpr[j]) * (1.0f + sc[j]) + sh[j];
;                 u32x2 w; w.x = pk2(h[0], h[1]); w.y = pk2(h[2], h[3]); *(GAS u32x2*)(H + (size_t)row * 1024 + 256 * j + 4 * lane) = w; }
;         }
.LBB0_1480:
	v_pk_mul_f32 v[54:55], v[100:101], v[100:101]
	v_pk_mul_f32 v[56:57], v[98:99], v[98:99]
	v_pk_mul_f32 v[46:47], v[132:133], v[132:133]
	v_pk_mul_f32 v[48:49], v[130:131], v[130:131]
	v_pk_mov_b32 v[58:59], v[56:57], v[54:55] op_sel:[1,0]
	v_mov_b32_e32 v57, v55
	v_pk_add_f32 v[54:55], v[58:59], v[56:57]
	v_pk_mov_b32 v[56:57], v[48:49], v[46:47] op_sel:[1,0]
	v_mov_b32_e32 v49, v47
	v_pk_add_f32 v[46:47], v[56:57], v[48:49]
	v_pk_add_f32 v[54:55], v[54:55], v[54:55] op_sel_hi:[0,1]
	v_pk_add_f32 v[46:47], v[46:47], v[46:47] op_sel_hi:[0,1]
	v_mul_f32_e32 v46, v134, v134
	v_pk_fma_f32 v[48:49], v[134:135], v[134:135], v[46:47] op_sel_hi:[1,1,0]
	v_mul_f32_e32 v46, v136, v136
	v_pk_fma_f32 v[56:57], v[136:137], v[136:137], v[46:47] op_sel_hi:[1,1,0]
	v_mul_f32_e32 v48, v138, v138
	v_mul_f32_e32 v56, v139, v139
	v_mul_f32_e32 v54, v140, v140
	v_mul_f32_e32 v46, v141, v141
	v_pk_add_f32 v[48:49], v[48:49], v[56:57]
	v_pk_add_f32 v[46:47], v[54:55], v[46:47]
	v_pk_add_f32 v[54:55], v[66:67], 1.0 op_sel_hi:[1,0]
	v_pk_add_f32 v[46:47], v[48:49], v[46:47]
	v_pk_add_f32 v[48:49], v[68:69], 1.0 op_sel_hi:[1,0]
	v_add_f32_e32 v46, v46, v47
	ds_bpermute_b32 v47, v190, v46
	s_add_i32 s0, s23, 8
	s_add_i32 s1, s23, -8
	s_cmp_lt_i32 s1, s17
	s_mov_b32 s23, s0
	s_waitcnt lgkmcnt(0)
	v_add_f32_e32 v46, v46, v47
	ds_bpermute_b32 v47, v191, v46
	v_mov_b64_e32 v[170:171], v[144:145]
	s_waitcnt vmcnt(3)
	v_mov_b64_e32 v[144:145], v[162:163]
	s_waitcnt lgkmcnt(0)
	v_add_f32_e32 v46, v46, v47
	ds_bpermute_b32 v47, v192, v46
	s_waitcnt lgkmcnt(0)
	v_add_f32_e32 v46, v46, v47
	ds_bpermute_b32 v47, v193, v46
	s_waitcnt lgkmcnt(0)
	v_add_f32_e32 v46, v46, v47
	ds_bpermute_b32 v47, v194, v46
	s_waitcnt lgkmcnt(0)
	v_add_f32_e32 v46, v46, v47
	ds_bpermute_b32 v47, v195, v46
	s_waitcnt lgkmcnt(0)
	v_add_f32_e32 v46, v46, v47
	v_fmamk_f32 v46, v46, 0x3a800000, v196
	v_mul_f32_e32 v47, 0x4b800000, v46
	v_cmp_gt_f32_e32 vcc, s27, v46
	s_nop 1
	v_cndmask_b32_e32 v46, v46, v47, vcc
	v_rsq_f32_e32 v56, v46
	v_lshl_add_u64 v[46:47], v[158:159], 0, s[2:3]
	v_mul_f32_e32 v57, 0x45800000, v56
	v_cndmask_b32_e32 v56, v56, v57, vcc
	v_pk_mul_f32 v[58:59], v[100:101], v[56:57] op_sel_hi:[1,0]
	v_pk_mul_f32 v[60:61], v[98:99], v[56:57] op_sel_hi:[1,0]
	v_pk_mul_f32 v[58:59], v[12:13], v[58:59]
	v_pk_mul_f32 v[60:61], v[10:11], v[60:61]
	v_pk_fma_f32 v[48:49], v[48:49], v[58:59], v[72:73]
	v_pk_fma_f32 v[54:55], v[54:55], v[60:61], v[70:71]
	v_pk_mul_f32 v[98:99], v[132:133], v[56:57] op_sel_hi:[1,0]
	v_pk_mul_f32 v[100:101], v[130:131], v[56:57] op_sel_hi:[1,0]
	v_cvt_pk_bf16_f32 v54, v54, v55
	v_cvt_pk_bf16_f32 v55, v48, v49
	v_pk_mul_f32 v[100:101], v[14:15], v[100:101]
	global_store_dwordx2 v[46:47], v[54:55], off
	v_pk_mul_f32 v[48:49], v[16:17], v[98:99]
	v_pk_add_f32 v[54:55], v[76:77], 1.0 op_sel_hi:[1,0]
	v_pk_add_f32 v[58:59], v[74:75], 1.0 op_sel_hi:[1,0]
	v_pk_fma_f32 v[48:49], v[54:55], v[48:49], v[80:81]
	v_pk_fma_f32 v[54:55], v[58:59], v[100:101], v[78:79]
	v_pk_add_f32 v[58:59], v[84:85], 1.0 op_sel_hi:[1,0]
	v_cvt_pk_bf16_f32 v54, v54, v55
	v_cvt_pk_bf16_f32 v55, v48, v49
	global_store_dwordx2 v[46:47], v[54:55], off offset:512
	v_pk_mul_f32 v[48:49], v[136:137], v[56:57] op_sel_hi:[1,0]
	v_pk_mul_f32 v[54:55], v[134:135], v[56:57] op_sel_hi:[1,0]
	v_pk_mul_f32 v[48:49], v[28:29], v[48:49]
	v_pk_mul_f32 v[54:55], v[26:27], v[54:55]
	v_pk_add_f32 v[60:61], v[82:83], 1.0 op_sel_hi:[1,0]
	s_waitcnt vmcnt(3)
	v_pk_fma_f32 v[48:49], v[58:59], v[48:49], v[92:93]
	v_pk_fma_f32 v[54:55], v[60:61], v[54:55], v[90:91]
	v_pk_add_f32 v[58:59], v[62:63], 1.0 op_sel_hi:[1,0]
	v_cvt_pk_bf16_f32 v54, v54, v55
	v_cvt_pk_bf16_f32 v55, v48, v49
	global_store_dwordx2 v[46:47], v[54:55], off offset:1024
	v_pk_mul_f32 v[48:49], v[140:141], v[56:57] op_sel_hi:[1,0]
	v_pk_mul_f32 v[54:55], v[138:139], v[56:57] op_sel_hi:[1,0]
	v_pk_mul_f32 v[48:49], v[32:33], v[48:49]
	v_pk_mul_f32 v[54:55], v[30:31], v[54:55]
	v_pk_add_f32 v[56:57], v[64:65], 1.0 op_sel_hi:[1,0]
	s_waitcnt vmcnt(3)
	v_pk_fma_f32 v[54:55], v[58:59], v[54:55], v[86:87]
	v_pk_fma_f32 v[48:49], v[56:57], v[48:49], v[88:89]
	v_cvt_pk_bf16_f32 v54, v54, v55
	v_cvt_pk_bf16_f32 v55, v48, v49
	global_store_dwordx2 v[46:47], v[54:55], off offset:1536
	s_mov_b64 vcc, s[98:99]
	s_cbranch_vccz .Leload_skip_2
	s_waitcnt vmcnt(8)
	v_lshlrev_b32_e32 v114, 16, v116
	v_and_b32_e32 v115, 0xffff0000, v116
	v_lshlrev_b32_e32 v116, 16, v117
	v_and_b32_e32 v117, 0xffff0000, v117
	v_lshlrev_b32_e32 v118, 16, v120
	v_and_b32_e32 v119, 0xffff0000, v120
	v_lshlrev_b32_e32 v120, 16, v121
	v_and_b32_e32 v121, 0xffff0000, v121
	v_lshlrev_b32_e32 v122, 16, v124
	v_and_b32_e32 v123, 0xffff0000, v124
	v_lshlrev_b32_e32 v124, 16, v125
	v_and_b32_e32 v125, 0xffff0000, v125
	v_lshlrev_b32_e32 v126, 16, v128
	v_and_b32_e32 v127, 0xffff0000, v128
	v_lshlrev_b32_e32 v128, 16, v129
	v_and_b32_e32 v129, 0xffff0000, v129

; #define LAS __attribute__((address_space(3)))
; #define MFMA32(a, b, c) __builtin_amdgcn_mfma_f32_32x32x16_bf16((a), (b), (c), 0, 0, 0)
; DI void qk_scores(const LAS uchar* Kb, int kc0, const bf16x8 (&qf)[4], f32x16 (&S)[2], int r, int hh) {
;     const int ksw = r & 15; const LAS uchar* kp = Kb + r * 256;
; #pragma unroll
;     for (int kb = 0; kb < 2; ++kb) {
;         bf16x8 kf[4];
; #pragma unroll
;         for (int s = 0; s < 4; ++s) kf[s] = *(const LAS bf16x8*)(kp + kb * 32 * 256 + (((kc0 + 2 * s + hh) ^ ksw) * 16));
;         { const f32x16 zero16 = {0.f, 0.f, 0.f, 0.f, 0.f, 0.f, 0.f, 0.f, 0.f, 0.f, 0.f, 0.f, 0.f, 0.f, 0.f, 0.f}; S[kb] = MFMA32(kf[0], qf[0], zero16); }
; #pragma unroll
;         for (int s = 1; s < 4; ++s) S[kb] = MFMA32(kf[s], qf[s], S[kb]);
;     }
; }
; template <bool HASNEXT>
; DI void attn_tile_pipe(const LAS uchar* Kn, int kc0, const LAS uchar* Vb, const bf16x8 (&qf)[4], f32x16 (&O)[4], f32x16 (&S)[2], f32x16 (&Sn)[2], float& m, float& l, int r, int hh, bool force) {
;     ...
; #pragma unroll
;     for (int step = 0; step < 4; ++step) {
;         const bf16x8 pf = __builtin_bit_cast(bf16x8, pw);
;         __builtin_amdgcn_sched_barrier(0);
; #pragma unroll
;         for (int d = 0; d < DVB; ++d) O[d] = MFMA32(vf[d], pf, O[d]);
;         __builtin_amdgcn_sched_barrier(0);
;         if (step < 3) {
; #pragma unroll
;             for (int d = 0; d < DVB; ++d) vf[d] = *(const LAS bf16x8*)(vp + d * 32 * 128 + (((2 * (step + 1) + hh) ^ vsw) * 16));
;             __builtin_amdgcn_sched_barrier(0);
;             ATT_P(step + 1);
;         }
;     }
;     ...
;     l += la0;
.LBB0_2027:
	v_exp_f32_e32 v114, v114
	v_exp_f32_e32 v115, v115
	v_exp_f32_e32 v116, v116
	v_exp_f32_e32 v117, v117
	v_exp_f32_e32 v118, v118
	v_exp_f32_e32 v119, v119
	v_exp_f32_e32 v120, v120
	v_exp_f32_e32 v121, v121
	v_cvt_pk_bf16_f32 v86, v114, v115
	v_cvt_pk_bf16_f32 v87, v116, v117
	v_cvt_pk_bf16_f32 v88, v118, v119
	v_cvt_pk_bf16_f32 v89, v120, v121
	s_waitcnt lgkmcnt(3)
	s_nop 0
	v_mfma_f32_32x32x16_bf16 v[50:65], v[78:81], v[86:89], v[50:65]
	ds_read_b128 v[78:81], v82 offset:49152
	s_waitcnt lgkmcnt(3)
	v_mfma_f32_32x32x16_bf16 v[34:49], v[74:77], v[86:89], v[34:49]
	ds_read_b128 v[74:77], v82 offset:53248
	s_waitcnt lgkmcnt(3)
	v_mfma_f32_32x32x16_bf16 v[18:33], v[70:73], v[86:89], v[18:33]
	ds_read_b128 v[70:73], v82 offset:57344
	s_waitcnt lgkmcnt(3)
	v_mfma_f32_32x32x16_bf16 v[2:17], v[66:69], v[86:89], v[2:17]
	ds_read_b128 v[66:69], v82 offset:61440
	v_exp_f32_e32 v122, v122
	v_exp_f32_e32 v123, v123
	v_exp_f32_e32 v124, v124
	v_exp_f32_e32 v125, v125
	v_exp_f32_e32 v126, v126
	v_exp_f32_e32 v127, v127
	v_exp_f32_e32 v128, v128
	v_exp_f32_e32 v129, v129
	v_cvt_pk_bf16_f32 v86, v122, v123
	v_cvt_pk_bf16_f32 v87, v124, v125
	v_cvt_pk_bf16_f32 v88, v126, v127
	v_cvt_pk_bf16_f32 v89, v128, v129
	s_waitcnt lgkmcnt(3)
	s_nop 0
	v_mfma_f32_32x32x16_bf16 v[50:65], v[78:81], v[86:89], v[50:65]
	ds_read_b128 v[78:81], v83 offset:49152
	s_waitcnt lgkmcnt(3)
	v_mfma_f32_32x32x16_bf16 v[34:49], v[74:77], v[86:89], v[34:49]
	ds_read_b128 v[74:77], v83 offset:53248
	s_waitcnt lgkmcnt(3)
	v_mfma_f32_32x32x16_bf16 v[18:33], v[70:73], v[86:89], v[18:33]
	ds_read_b128 v[70:73], v83 offset:57344
	s_waitcnt lgkmcnt(3)
	v_mfma_f32_32x32x16_bf16 v[2:17], v[66:69], v[86:89], v[2:17]
	ds_read_b128 v[66:69], v83 offset:61440
	v_exp_f32_e32 v147, v98
	v_exp_f32_e32 v148, v99
	v_exp_f32_e32 v149, v100
	v_exp_f32_e32 v150, v101
	v_exp_f32_e32 v151, v102
	v_exp_f32_e32 v152, v103
	v_exp_f32_e32 v153, v104
	v_exp_f32_e32 v154, v105
	v_cvt_pk_bf16_f32 v86, v147, v148
	v_cvt_pk_bf16_f32 v87, v149, v150
	v_cvt_pk_bf16_f32 v88, v151, v152
	v_cvt_pk_bf16_f32 v89, v153, v154
	s_waitcnt lgkmcnt(3)
	s_nop 0
	v_mfma_f32_32x32x16_bf16 v[50:65], v[78:81], v[86:89], v[50:65]
	ds_read_b128 v[78:81], v84 offset:49152
	s_waitcnt lgkmcnt(3)
	v_mfma_f32_32x32x16_bf16 v[34:49], v[74:77], v[86:89], v[34:49]
	ds_read_b128 v[74:77], v84 offset:53248
	s_waitcnt lgkmcnt(3)
	v_mfma_f32_32x32x16_bf16 v[18:33], v[70:73], v[86:89], v[18:33]
	ds_read_b128 v[70:73], v84 offset:57344
	s_waitcnt lgkmcnt(3)
	v_mfma_f32_32x32x16_bf16 v[2:17], v[66:69], v[86:89], v[2:17]
	ds_read_b128 v[66:69], v84 offset:61440
	v_exp_f32_e32 v155, v106
	v_exp_f32_e32 v156, v107
	v_exp_f32_e32 v157, v108
	v_exp_f32_e32 v158, v109
	v_exp_f32_e32 v110, v110
	v_exp_f32_e32 v111, v111
	v_exp_f32_e32 v112, v112
	v_exp_f32_e32 v113, v113
	v_cvt_pk_bf16_f32 v82, v155, v156
	v_cvt_pk_bf16_f32 v83, v157, v158
	v_cvt_pk_bf16_f32 v84, v110, v111
	v_cvt_pk_bf16_f32 v85, v112, v113
	s_waitcnt lgkmcnt(3)
	s_nop 0
	v_mfma_f32_32x32x16_bf16 v[50:65], v[78:81], v[82:85], v[50:65]
	s_waitcnt lgkmcnt(2)
	v_mfma_f32_32x32x16_bf16 v[34:49], v[74:77], v[82:85], v[34:49]
	s_waitcnt lgkmcnt(1)
	v_mfma_f32_32x32x16_bf16 v[18:33], v[70:73], v[82:85], v[18:33]
	s_waitcnt lgkmcnt(0)
	v_mfma_f32_32x32x16_bf16 v[2:17], v[66:69], v[82:85], v[2:17]
	v_add_u32_e32 v78, s1, v198
	v_add_u32_e32 v70, v78, v199
	s_waitcnt vmcnt(0)
	s_waitcnt vmcnt(0)
	s_barrier
	ds_read_b128 v[66:69], v70
	v_add_u32_e32 v79, v78, v200
	ds_read_b128 v[70:73], v70 offset:8192
	v_add_u32_e32 v80, v78, v201
	v_add_u32_e32 v78, v78, v202
	s_waitcnt lgkmcnt(1)
	v_mfma_f32_32x32x16_bf16 v[82:97], v[66:69], v[134:137], v[238:253]
	ds_read_b128 v[66:69], v79
	ds_read_b128 v[74:77], v80
	ds_read_b128 v[98:101], v79 offset:8192
	s_add_u32 s2, s2, 0x100
	s_addc_u32 s3, s3, 0
	s_add_u32 s4, s4, 0x20000
	s_addc_u32 s5, s5, 0
	s_cmp_eq_u32 s0, 0x410000
	s_waitcnt lgkmcnt(2)
	v_mfma_f32_32x32x16_bf16 v[82:97], v[66:69], v[130:133], v[82:97]
	v_add_f32_e32 v66, 0, v114
	v_add_f32_e32 v66, v115, v66
	v_add_f32_e32 v79, v116, v66
	ds_read_b128 v[102:105], v80 offset:8192
	ds_read_b128 v[66:69], v78
	ds_read_b128 v[106:109], v78 offset:8192
	s_waitcnt lgkmcnt(4)
	v_mfma_f32_32x32x16_bf16 v[82:97], v[74:77], v[142:145], v[82:97]
	v_add_f32_e32 v74, v117, v79
	v_add_f32_e32 v74, v118, v74
	v_add_f32_e32 v74, v119, v74
	v_add_f32_e32 v74, v120, v74
	v_add_f32_e32 v74, v121, v74
	v_add_f32_e32 v74, v122, v74
	v_add_f32_e32 v74, v123, v74
	s_waitcnt lgkmcnt(1)
	v_mfma_f32_32x32x16_bf16 v[82:97], v[66:69], v[138:141], v[82:97]
	v_add_f32_e32 v66, v124, v74
	v_add_f32_e32 v66, v125, v66
	v_add_f32_e32 v66, v126, v66
	v_add_f32_e32 v66, v127, v66
	v_add_f32_e32 v66, v128, v66
	v_add_f32_e32 v66, v129, v66
	v_add_f32_e32 v114, v147, v66
	v_mfma_f32_32x32x16_bf16 v[66:81], v[70:73], v[134:137], v[238:253]
	v_add_f32_e32 v114, v148, v114
	v_add_f32_e32 v114, v149, v114
	v_add_f32_e32 v114, v150, v114
	v_add_f32_e32 v114, v151, v114
	v_add_f32_e32 v114, v152, v114
	v_add_f32_e32 v114, v153, v114
	v_add_f32_e32 v114, v154, v114
	v_mfma_f32_32x32x16_bf16 v[66:81], v[98:101], v[130:133], v[66:81]
	v_add_f32_e32 v98, v155, v114
	v_add_f32_e32 v98, v156, v98
	v_add_f32_e32 v98, v157, v98
	v_add_f32_e32 v98, v158, v98
	v_add_f32_e32 v98, v110, v98
	v_add_f32_e32 v98, v111, v98
	v_add_f32_e32 v98, v112, v98
	v_mfma_f32_32x32x16_bf16 v[66:81], v[102:105], v[142:145], v[66:81]
	v_add_f32_e32 v98, v113, v98
	v_add_f32_e32 v213, v146, v98
	s_waitcnt lgkmcnt(0)
	v_mfma_f32_32x32x16_bf16 v[66:81], v[106:109], v[138:141], v[66:81]
	s_cbranch_scc1 .Lattn_unshift

; #define GAS __attribute__((address_space(1)))
; DI unsigned pk2(float lo, float hi) { f32x2_t v = {lo, hi}; bf16x2_t b = __builtin_convertvector(v, bf16x2_t); return __builtin_bit_cast(unsigned, b); }
; DI void phase_e(const Ctx& C, int nslab, int has_post, int pl, int ps, float pw, int has_pre, int ql, int qs, int nrows,
;                 const GAS float* xsrc, const GAS float* csrc, GAS float* xdst, GAS float* cdst, bool xs16, bool xd16) {
;     ...
;         if (has_pre) {
;             float ss = 0.f;
; #pragma unroll
;             for (int j = 0; j < 4; ++j) ss += (v[j][0] * v[j][0] + v[j][1] * v[j][1]) + (v[j][2] * v[j][2] + v[j][3] * v[j][3]);
;             const float r = rsqrtf(wave_sum(ss) * (1.0f / 1024.0f) + EPS);
; #pragma unroll
;             for (int j = 0; j < 4; ++j) { const f32x4 h = ((v[j] * r) * gpr[j]) * (1.0f + sc[j]) + sh[j];
;                 u32x2 w; w.x = pk2(h[0], h[1]); w.y = pk2(h[2], h[3]); *(GAS u32x2*)(H + (size_t)row * 1024 + 256 * j + 4 * lane) = w; }
;         }
.LBB0_2209:
	v_pk_mul_f32 v[54:55], v[132:133], v[132:133]
	v_pk_mul_f32 v[56:57], v[130:131], v[130:131]
	v_pk_mul_f32 v[50:51], v[136:137], v[136:137]
	v_pk_mul_f32 v[52:53], v[134:135], v[134:135]
	v_pk_mov_b32 v[58:59], v[56:57], v[54:55] op_sel:[1,0]
	v_mov_b32_e32 v57, v55
	v_pk_add_f32 v[54:55], v[58:59], v[56:57]
	v_pk_mov_b32 v[56:57], v[52:53], v[50:51] op_sel:[1,0]
	v_mov_b32_e32 v53, v51
	v_pk_add_f32 v[50:51], v[56:57], v[52:53]
	v_pk_add_f32 v[54:55], v[54:55], v[54:55] op_sel_hi:[0,1]
	v_pk_add_f32 v[50:51], v[50:51], v[50:51] op_sel_hi:[0,1]
	v_mul_f32_e32 v50, v138, v138
	v_pk_fma_f32 v[52:53], v[138:139], v[138:139], v[50:51] op_sel_hi:[1,1,0]
	v_mul_f32_e32 v50, v140, v140
	v_pk_fma_f32 v[56:57], v[140:141], v[140:141], v[50:51] op_sel_hi:[1,1,0]
	v_mul_f32_e32 v52, v142, v142
	v_mul_f32_e32 v56, v143, v143
	v_mul_f32_e32 v54, v144, v144
	v_mul_f32_e32 v50, v145, v145
	v_pk_add_f32 v[52:53], v[52:53], v[56:57]
	v_pk_add_f32 v[50:51], v[54:55], v[50:51]
	s_waitcnt vmcnt(10)
	v_pk_add_f32 v[54:55], v[70:71], 1.0 op_sel_hi:[1,0]
	v_pk_add_f32 v[50:51], v[52:53], v[50:51]
	v_pk_add_f32 v[52:53], v[72:73], 1.0 op_sel_hi:[1,0]
	v_add_f32_e32 v50, v50, v51
	ds_bpermute_b32 v51, v191, v50
	s_add_i32 s16, s16, 8
	s_cmp_lt_i32 s16, s17
	s_waitcnt lgkmcnt(0)
	v_add_f32_e32 v50, v50, v51
	ds_bpermute_b32 v51, v192, v50
	s_waitcnt lgkmcnt(0)
	v_add_f32_e32 v50, v50, v51
	ds_bpermute_b32 v51, v193, v50
	s_waitcnt lgkmcnt(0)
	v_add_f32_e32 v50, v50, v51
	ds_bpermute_b32 v51, v194, v50
	s_waitcnt lgkmcnt(0)
	v_add_f32_e32 v50, v50, v51
	ds_bpermute_b32 v51, v195, v50
	s_waitcnt lgkmcnt(0)
	v_add_f32_e32 v50, v50, v51
	ds_bpermute_b32 v51, v196, v50
	s_waitcnt lgkmcnt(0)
	v_add_f32_e32 v50, v50, v51
	v_fmamk_f32 v50, v50, 0x3a800000, v197
	v_mul_f32_e32 v51, 0x4b800000, v50
	v_cmp_gt_f32_e32 vcc, s22, v50
	s_nop 1
	v_cndmask_b32_e32 v50, v50, v51, vcc
	v_rsq_f32_e32 v56, v50
	v_lshl_add_u64 v[50:51], v[162:163], 0, s[8:9]
	v_mul_f32_e32 v57, 0x45800000, v56
	v_cndmask_b32_e32 v56, v56, v57, vcc
	v_pk_mul_f32 v[58:59], v[132:133], v[56:57] op_sel_hi:[1,0]
	v_pk_mul_f32 v[60:61], v[130:131], v[56:57] op_sel_hi:[1,0]
	v_pk_mul_f32 v[58:59], v[12:13], v[58:59]
	v_pk_mul_f32 v[60:61], v[10:11], v[60:61]
	s_waitcnt vmcnt(9)
	v_pk_fma_f32 v[52:53], v[52:53], v[58:59], v[76:77]
	v_pk_fma_f32 v[54:55], v[54:55], v[60:61], v[74:75]
	v_pk_mul_f32 v[62:63], v[136:137], v[56:57] op_sel_hi:[1,0]
	v_pk_mul_f32 v[64:65], v[134:135], v[56:57] op_sel_hi:[1,0]
	v_cvt_pk_bf16_f32 v54, v54, v55
	v_cvt_pk_bf16_f32 v55, v52, v53
	v_pk_mul_f32 v[64:65], v[14:15], v[64:65]
	global_store_dwordx2 v[50:51], v[54:55], off
	v_pk_mul_f32 v[52:53], v[16:17], v[62:63]
	s_waitcnt vmcnt(6)
	v_pk_add_f32 v[54:55], v[80:81], 1.0 op_sel_hi:[1,0]
	v_pk_add_f32 v[58:59], v[78:79], 1.0 op_sel_hi:[1,0]
	v_pk_fma_f32 v[52:53], v[54:55], v[52:53], v[84:85]
	v_pk_fma_f32 v[54:55], v[58:59], v[64:65], v[82:83]
	s_waitcnt vmcnt(4)
	v_pk_add_f32 v[58:59], v[88:89], 1.0 op_sel_hi:[1,0]
	v_cvt_pk_bf16_f32 v54, v54, v55
	v_cvt_pk_bf16_f32 v55, v52, v53
	global_store_dwordx2 v[50:51], v[54:55], off offset:512
	v_pk_mul_f32 v[52:53], v[140:141], v[56:57] op_sel_hi:[1,0]
	v_pk_mul_f32 v[54:55], v[138:139], v[56:57] op_sel_hi:[1,0]
	v_pk_mul_f32 v[52:53], v[28:29], v[52:53]
	v_pk_mul_f32 v[54:55], v[26:27], v[54:55]
	v_pk_add_f32 v[60:61], v[86:87], 1.0 op_sel_hi:[1,0]
	s_waitcnt vmcnt(3)
	v_pk_fma_f32 v[52:53], v[58:59], v[52:53], v[96:97]
	v_pk_fma_f32 v[54:55], v[60:61], v[54:55], v[94:95]
	v_pk_add_f32 v[58:59], v[66:67], 1.0 op_sel_hi:[1,0]
	v_cvt_pk_bf16_f32 v54, v54, v55
	v_cvt_pk_bf16_f32 v55, v52, v53
	global_store_dwordx2 v[50:51], v[54:55], off offset:1024
	v_pk_mul_f32 v[52:53], v[144:145], v[56:57] op_sel_hi:[1,0]
	v_pk_mul_f32 v[54:55], v[142:143], v[56:57] op_sel_hi:[1,0]
	v_pk_mul_f32 v[52:53], v[32:33], v[52:53]
	v_pk_mul_f32 v[54:55], v[30:31], v[54:55]
	v_pk_add_f32 v[56:57], v[68:69], 1.0 op_sel_hi:[1,0]
	s_waitcnt vmcnt(3)
	v_pk_fma_f32 v[54:55], v[58:59], v[54:55], v[90:91]
	v_pk_fma_f32 v[52:53], v[56:57], v[52:53], v[92:93]
	v_cvt_pk_bf16_f32 v54, v54, v55
	v_cvt_pk_bf16_f32 v55, v52, v53
	global_store_dwordx2 v[50:51], v[54:55], off offset:1536
	s_mov_b64 vcc, s[98:99]
	s_cbranch_vccz .Leload_skip_3
	s_waitcnt vmcnt(8)
	v_lshlrev_b32_e32 v114, 16, v116
	v_and_b32_e32 v115, 0xffff0000, v116
	v_lshlrev_b32_e32 v116, 16, v117
	v_and_b32_e32 v117, 0xffff0000, v117
	v_lshlrev_b32_e32 v118, 16, v120
	v_and_b32_e32 v119, 0xffff0000, v120
	v_lshlrev_b32_e32 v120, 16, v121
	v_and_b32_e32 v121, 0xffff0000, v121
	v_lshlrev_b32_e32 v122, 16, v124
	v_and_b32_e32 v123, 0xffff0000, v124
	v_lshlrev_b32_e32 v124, 16, v125
	v_and_b32_e32 v125, 0xffff0000, v125
	v_lshlrev_b32_e32 v126, 16, v128
	v_and_b32_e32 v127, 0xffff0000, v128
	v_lshlrev_b32_e32 v128, 16, v129
	v_and_b32_e32 v129, 0xffff0000, v129
.Leload_skip_3:
	v_mov_b64_e32 v[52:53], v[48:49]
	v_mov_b64_e32 v[56:57], v[44:45]
	v_mov_b64_e32 v[60:61], v[40:41]
	v_mov_b64_e32 v[64:65], v[36:37]
	v_mov_b64_e32 v[50:51], v[46:47]
	v_mov_b64_e32 v[54:55], v[42:43]
	v_mov_b64_e32 v[58:59], v[38:39]
	v_mov_b64_e32 v[62:63], v[34:35]
	v_mov_b64_e32 v[46:47], v[126:127]
	v_mov_b64_e32 v[42:43], v[122:123]
	v_mov_b64_e32 v[38:39], v[118:119]
	v_mov_b64_e32 v[34:35], v[114:115]
	v_mov_b64_e32 v[48:49], v[128:129]
	v_mov_b64_e32 v[44:45], v[124:125]
	v_mov_b64_e32 v[40:41], v[120:121]
	v_mov_b64_e32 v[36:37], v[116:117]
	v_mov_b64_e32 v[130:131], v[154:155]
	v_mov_b64_e32 v[132:133], v[152:153]
	v_mov_b64_e32 v[134:135], v[150:151]
	v_mov_b64_e32 v[136:137], v[148:149]
	v_mov_b64_e32 v[154:155], v[172:173]
	v_mov_b64_e32 v[152:153], v[170:171]
	v_mov_b64_e32 v[150:151], v[168:169]
	v_mov_b64_e32 v[148:149], v[166:167]
	s_cbranch_scc0 .LBB0_2222
.LBB0_2210:
	s_mov_b64 s[98:99], 0
	s_add_i32 s6, s18, s16
	s_add_i32 s0, s16, 16
	s_cmp_ge_i32 s0, s17
	s_cbranch_scc1 .LBB0_2216
	s_add_i32 s10, s6, 16
	s_cmpk_gt_i32 s10, 0x7fff
	s_mov_b64 s[12:13], -1
	s_cbranch_scc0 .LBB0_2213
	s_add_i32 s0, s6, 0xffff8010
	s_lshl_b64 s[8:9], s[0:1], 12
	v_lshl_add_u64 v[126:127], v[164:165], 0, s[8:9]
	global_load_dwordx4 v[114:117], v[126:127], off nt
	global_load_dwordx4 v[118:121], v[126:127], off offset:1024 nt
	global_load_dwordx4 v[122:125], v[126:127], off offset:2048 nt
	s_nop 0
	global_load_dwordx4 v[126:129], v[126:127], off offset:3072 nt
	s_mov_b32 s11, s1
	s_lshl_b64 s[8:9], s[10:11], 11
	s_mov_b64 s[12:13], 0
.LBB0_2213:
	s_andn2_b64 vcc, exec, s[12:13]
	s_cbranch_vccnz .LBB0_2215
	s_ashr_i32 s11, s10, 31
	s_lshl_b64 s[8:9], s[10:11], 11
	s_waitcnt vmcnt(3)
	v_lshl_add_u64 v[114:115], v[156:157], 0, s[8:9]
	global_load_dwordx2 v[116:117], v[114:115], off nt
	global_load_dwordx2 v[120:121], v[114:115], off offset:512 nt
	global_load_dwordx2 v[124:125], v[114:115], off offset:1024 nt
	global_load_dwordx2 v[128:129], v[114:115], off offset:1536 nt
	s_mov_b64 s[98:99], -1

; #define GAS __attribute__((address_space(1)))
; DI unsigned pk2(float lo, float hi) { f32x2_t v = {lo, hi}; bf16x2_t b = __builtin_convertvector(v, bf16x2_t); return __builtin_bit_cast(unsigned, b); }
; DI float bflo(unsigned w) { return __uint_as_float(w << 16); }
; DI float bfhi(unsigned w) { return __uint_as_float(w & 0xffff0000u); }
; DI void phase_e(const Ctx& C, int nslab, int has_post, int pl, int ps, float pw, int has_pre, int ql, int qs, int nrows,
;                 const GAS float* xsrc, const GAS float* csrc, GAS float* xdst, GAS float* cdst, bool xs16, bool xd16) {
;     ...
;         if (has_post) {
;             f32x4 y[4]; float ss = 0.f;
; #pragma unroll
;             for (int j = 0; j < 4; ++j) {
;                 if (isx || nslab == 0) { y[j] = (f32x4){bflo(yw[j].x), bfhi(yw[j].x), bflo(yw[j].y), bfhi(yw[j].y)}; }
;                 else { y[j] = (f32x4){0.f, 0.f, 0.f, 0.f};
;                     for (int s = 0; s < nslab; ++s) { const u32x2 w = *(const GAS u32x2*)(YS + ((size_t)s * MC + (row - MX)) * 1024 + 256 * j + 4 * lane); y[j] += (f32x4){bflo(w.x), bfhi(w.x), bflo(w.y), bfhi(w.y)}; } }
;                 ss += (y[j][0] * y[j][0] + y[j][1] * y[j][1]) + (y[j][2] * y[j][2] + y[j][3] * y[j][3]); }
;             const float r = rsqrtf(wave_sum(ss) * (1.0f / 1024.0f) + EPS);
;             if (isx && xd16) { GAS bf16* d16 = (GAS bf16*)xdst + (size_t)row * 1024;
; #pragma unroll
;                 for (int j = 0; j < 4; ++j) { v[j] += pw * gt[j] * ((y[j] * r) * gpo[j]); u32x2 w; w.x = pk2(v[j][0], v[j][1]); w.y = pk2(v[j][2], v[j][3]); __builtin_nontemporal_store(w, (GAS u32x2*)(d16 + 256 * j + 4 * lane));
;                     v[j] = (f32x4){bflo(w.x), bfhi(w.x), bflo(w.y), bfhi(w.y)}; }
;             } else { GAS float* dst = isx ? xdst + (size_t)row * 1024 : cdst + (size_t)(row - MX) * 1024;
; #pragma unroll
;                 for (int j = 0; j < 4; ++j) { v[j] += pw * gt[j] * ((y[j] * r) * gpo[j]); __builtin_nontemporal_store(v[j], (GAS f32x4*)(dst + 256 * j + 4 * lane)); } }
.LBB0_2444:
	v_lshlrev_b32_e32 v123, 16, v99
	v_lshlrev_b32_e32 v122, 16, v98
	v_and_b32_e32 v99, 0xffff0000, v99
	v_and_b32_e32 v98, 0xffff0000, v98
	v_pk_mul_f32 v[124:125], v[98:99], v[98:99]
	v_lshlrev_b32_e32 v127, 16, v91
	v_pk_fma_f32 v[124:125], v[122:123], v[122:123], v[124:125]
	v_lshlrev_b32_e32 v126, 16, v90
	v_and_b32_e32 v91, 0xffff0000, v91
	v_and_b32_e32 v90, 0xffff0000, v90
	v_pk_add_f32 v[124:125], v[124:125], v[124:125] op_sel_hi:[0,1]
	v_pk_mul_f32 v[128:129], v[90:91], v[90:91]
	v_lshlrev_b32_e32 v130, 16, v86
	v_and_b32_e32 v131, 0xffff0000, v86
	v_lshlrev_b32_e32 v86, 16, v87
	v_lshlrev_b32_e32 v132, 16, v84
	v_pk_fma_f32 v[128:129], v[126:127], v[126:127], v[128:129]
	v_mul_f32_e32 v133, v130, v130
	v_mul_f32_e32 v135, v131, v131
	v_and_b32_e32 v87, 0xffff0000, v87
	v_mul_f32_e32 v124, v86, v86
	v_mov_b32_e32 v134, v132
	v_pk_add_f32 v[128:129], v[128:129], v[128:129] op_sel_hi:[0,1]
	v_pk_fma_f32 v[136:137], v[86:87], v[86:87], v[124:125] op_sel_hi:[1,1,0]
	v_and_b32_e32 v121, 0xffff0000, v84
	v_lshlrev_b32_e32 v84, 16, v85
	v_and_b32_e32 v85, 0xffff0000, v85
	v_pk_add_f32 v[134:135], v[132:133], v[134:135]
	v_mul_f32_e32 v136, v121, v121
	v_mul_f32_e32 v128, v84, v84
	v_mul_f32_e32 v124, v85, v85
	v_mul_f32_e32 v138, v132, v132
	v_mov_b32_e32 v139, v135
	v_pk_add_f32 v[134:135], v[138:139], v[136:137]
	v_pk_add_f32 v[124:125], v[128:129], v[124:125]
	s_add_i32 s2, s19, 0xffff8000
	v_pk_add_f32 v[124:125], v[134:135], v[124:125]
	s_ashr_i32 s6, s19, 31
	v_add_f32_e32 v124, v124, v125
	ds_bpermute_b32 v125, v114, v124
	s_cmp_lt_i32 s19, 0x8000
	v_mov_b32_e32 v136, v123
	v_mov_b32_e32 v123, v98
	s_cselect_b32 s7, s6, 0
	s_waitcnt lgkmcnt(0)
	v_add_f32_e32 v124, v124, v125
	ds_bpermute_b32 v125, v115, v124
	s_cselect_b32 s6, s19, s2
	v_mov_b32_e32 v137, v99
	s_cselect_b32 s2, s75, s1
	s_cselect_b32 s8, s74, s0
	s_waitcnt lgkmcnt(0)
	v_add_f32_e32 v124, v124, v125
	ds_bpermute_b32 v125, v116, v124
	s_lshl_b64 s[6:7], s[6:7], 12
	s_waitcnt vmcnt(1)
	v_pk_mul_f32 v[134:135], v[50:51], 0.5 op_sel_hi:[1,0]
	s_add_u32 s6, s8, s6
	v_pk_mul_f32 v[128:129], v[52:53], 0.5 op_sel_hi:[1,0]
	s_waitcnt lgkmcnt(0)
	v_add_f32_e32 v124, v124, v125
	ds_bpermute_b32 v125, v117, v124
	s_addc_u32 s7, s2, s7
	v_mov_b32_e32 v133, v121
	s_add_i32 s14, s14, 8
	s_cmp_lt_i32 s14, s15
	s_waitcnt lgkmcnt(0)
	v_add_f32_e32 v124, v124, v125
	ds_bpermute_b32 v125, v118, v124
	s_waitcnt lgkmcnt(0)
	v_add_f32_e32 v124, v124, v125
	ds_bpermute_b32 v125, v119, v124
	s_waitcnt lgkmcnt(0)
	v_add_f32_e32 v124, v124, v125
	v_fmamk_f32 v124, v124, 0x3a800000, v120
	v_mul_f32_e32 v125, 0x4b800000, v124
	v_cmp_gt_f32_e32 vcc, s18, v124
	s_nop 1
	v_cndmask_b32_e32 v124, v124, v125, vcc
	v_rsq_f32_e32 v124, v124
	s_nop 0
	v_mul_f32_e32 v125, 0x45800000, v124
	v_cndmask_b32_e32 v124, v124, v125, vcc
	v_pk_mul_f32 v[98:99], v[122:123], v[124:125] op_sel_hi:[1,0]
	v_pk_mul_f32 v[136:137], v[136:137], v[124:125] op_sel_hi:[1,0]
	v_pk_mul_f32 v[98:99], v[2:3], v[98:99]
	v_pk_mul_f32 v[122:123], v[4:5], v[136:137]
	v_pk_fma_f32 v[30:31], v[134:135], v[98:99], v[30:31]
	v_mov_b32_e32 v98, v127
	v_mov_b32_e32 v99, v91
	v_mov_b32_e32 v127, v90
	v_pk_fma_f32 v[32:33], v[128:129], v[122:123], v[32:33]
	v_pk_mul_f32 v[98:99], v[98:99], v[124:125] op_sel_hi:[1,0]
	v_pk_mul_f32 v[90:91], v[126:127], v[124:125] op_sel_hi:[1,0]
	global_store_dwordx4 v82, v[30:33], s[6:7] nt
	v_pk_mul_f32 v[90:91], v[6:7], v[90:91]
	v_pk_mul_f32 v[98:99], v[8:9], v[98:99]
	v_pk_mul_f32 v[30:31], v[56:57], 0.5 op_sel_hi:[1,0]
	v_pk_mul_f32 v[32:33], v[54:55], 0.5 op_sel_hi:[1,0]
	v_pk_fma_f32 v[28:29], v[30:31], v[98:99], v[28:29]
	v_pk_fma_f32 v[26:27], v[32:33], v[90:91], v[26:27]
	v_pk_mul_f32 v[30:31], v[86:87], v[124:125] op_sel_hi:[1,0]
	v_pk_mul_f32 v[32:33], v[130:131], v[124:125] op_sel_hi:[1,0]
	global_store_dwordx4 v82, v[26:29], s[6:7] offset:1024 nt
	v_pk_mul_f32 v[32:33], v[10:11], v[32:33]
	v_pk_mul_f32 v[30:31], v[12:13], v[30:31]
	v_pk_mul_f32 v[26:27], v[60:61], 0.5 op_sel_hi:[1,0]
	v_pk_mul_f32 v[28:29], v[58:59], 0.5 op_sel_hi:[1,0]
	v_pk_fma_f32 v[24:25], v[26:27], v[30:31], v[24:25]
	v_pk_fma_f32 v[22:23], v[28:29], v[32:33], v[22:23]
	v_pk_mul_f32 v[26:27], v[84:85], v[124:125] op_sel_hi:[1,0]
	v_pk_mul_f32 v[28:29], v[132:133], v[124:125] op_sel_hi:[1,0]
	global_store_dwordx4 v82, v[22:25], s[6:7] offset:2048 nt
	v_pk_mul_f32 v[28:29], v[14:15], v[28:29]
	v_pk_mul_f32 v[26:27], v[16:17], v[26:27]
	s_waitcnt vmcnt(3)
	v_pk_mul_f32 v[22:23], v[64:65], 0.5 op_sel_hi:[1,0]
	v_pk_mul_f32 v[24:25], v[62:63], 0.5 op_sel_hi:[1,0]
	v_pk_fma_f32 v[20:21], v[22:23], v[26:27], v[20:21]
	v_pk_fma_f32 v[18:19], v[24:25], v[28:29], v[18:19]
	global_store_dwordx4 v82, v[18:21], s[6:7] offset:3072 nt
	s_mov_b64 vcc, s[98:99]
	s_cbranch_vccz .Leload_skip_4
	s_waitcnt vmcnt(4)
	v_lshlrev_b32_e32 v66, 16, v68
	v_and_b32_e32 v67, 0xffff0000, v68
	v_lshlrev_b32_e32 v68, 16, v69
	v_and_b32_e32 v69, 0xffff0000, v69
	v_lshlrev_b32_e32 v70, 16, v72
	v_and_b32_e32 v71, 0xffff0000, v72
	v_lshlrev_b32_e32 v72, 16, v73
	v_and_b32_e32 v73, 0xffff0000, v73
	v_lshlrev_b32_e32 v74, 16, v76
	v_and_b32_e32 v75, 0xffff0000, v76
	v_lshlrev_b32_e32 v76, 16, v77
	v_and_b32_e32 v77, 0xffff0000, v77
	v_lshlrev_b32_e32 v78, 16, v80
	v_and_b32_e32 v79, 0xffff0000, v80
	v_lshlrev_b32_e32 v80, 16, v81
	v_and_b32_e32 v81, 0xffff0000, v81
; DI void phase_e(const Ctx& C, int nslab, int has_post, int pl, int ps, float pw, int has_pre, int ql, int qs, int nrows,
;                 const GAS float* xsrc, const GAS float* csrc, GAS float* xdst, GAS float* cdst, bool xs16, bool xd16) {
;     ...
;     int i = C.wave;
;     if (i < total) E_LOAD(i, vN, yN);
;     if (i + 8 < total) E_LOAD(i + 8, vM, yM);
;     for (; i < total; i += 8) {
;         const int row = E_ROW(i);
;         const bool isx = row < MX; const int mi = isx ? (row >> 13) : 4;
;         f32x4 v[4]; u32x2 yw[4];
; #pragma unroll
;         for (int j = 0; j < 4; ++j) { v[j] = vN[j]; yw[j] = yN[j]; vN[j] = vM[j]; yN[j] = yM[j]; }
;         if (i + 16 < total) E_LOAD(i + 16, vM, yM);
.Leload_skip_4:
	v_mov_b64_e32 v[22:23], v[42:43]
	v_mov_b64_e32 v[26:27], v[38:39]
	v_mov_b64_e32 v[18:19], v[46:47]
	v_mov_b64_e32 v[30:31], v[34:35]
	v_mov_b64_e32 v[20:21], v[48:49]
	v_mov_b64_e32 v[24:25], v[44:45]
	v_mov_b64_e32 v[28:29], v[40:41]
	v_mov_b64_e32 v[32:33], v[36:37]
	v_mov_b64_e32 v[46:47], v[78:79]
	v_mov_b64_e32 v[42:43], v[74:75]
	v_mov_b64_e32 v[38:39], v[70:71]
	v_mov_b64_e32 v[34:35], v[66:67]
	v_mov_b64_e32 v[48:49], v[80:81]
	v_mov_b64_e32 v[44:45], v[76:77]
	v_mov_b64_e32 v[40:41], v[72:73]
	v_mov_b64_e32 v[36:37], v[68:69]
	v_mov_b64_e32 v[84:85], v[96:97]
	v_mov_b64_e32 v[86:87], v[94:95]
	v_mov_b64_e32 v[90:91], v[92:93]
	v_mov_b64_e32 v[98:99], v[88:89]
	v_mov_b64_e32 v[96:97], v[112:113]
	v_mov_b64_e32 v[94:95], v[110:111]
	v_mov_b64_e32 v[92:93], v[108:109]
	v_mov_b64_e32 v[88:89], v[106:107]
	s_cbranch_scc0 .LBB0_2453
.LBB0_2445:
	s_mov_b64 s[98:99], 0
	s_add_i32 s19, s16, s14
	s_add_i32 s2, s14, 16
	s_cmp_ge_i32 s2, s15
	s_cbranch_scc1 .LBB0_2451
	s_add_i32 s8, s19, 16
	s_cmpk_gt_i32 s8, 0x7fff
	s_mov_b64 s[10:11], -1
	s_cbranch_scc0 .LBB0_2448
	s_add_i32 s2, s19, 0xffff8010
	s_lshl_b64 s[6:7], s[2:3], 12
	v_lshl_add_u64 v[106:107], v[104:105], 0, s[6:7]
	global_load_dwordx4 v[66:69], v[106:107], off nt
	global_load_dwordx4 v[70:73], v[106:107], off offset:1024 nt
	global_load_dwordx4 v[74:77], v[106:107], off offset:2048 nt
	global_load_dwordx4 v[78:81], v[106:107], off offset:3072 nt
	s_mov_b32 s9, s3
	s_lshl_b64 s[6:7], s[8:9], 11
	s_mov_b64 s[10:11], 0
.LBB0_2448:
	s_andn2_b64 vcc, exec, s[10:11]
	s_cbranch_vccnz .LBB0_2450
	s_ashr_i32 s9, s8, 31
	s_lshl_b64 s[6:7], s[8:9], 11
	s_waitcnt vmcnt(3)
	v_lshl_add_u64 v[66:67], v[100:101], 0, s[6:7]
	global_load_dwordx2 v[68:69], v[66:67], off nt
	global_load_dwordx2 v[72:73], v[66:67], off offset:512 nt
	global_load_dwordx2 v[76:77], v[66:67], off offset:1024 nt
	global_load_dwordx2 v[80:81], v[66:67], off offset:1536 nt
	s_mov_b64 s[98:99], -1

; #define LAS __attribute__((address_space(3)))
; __global__ void __launch_bounds__(512, 2) fwd_kernel(Args a) {
;     extern __shared__ __attribute__((aligned(16))) unsigned char lds_raw[];
;     Ctx C;
;     C.lds = (LAS uchar*)lds_raw; C.tid = threadIdx.x; C.lane = C.tid & 63; C.wave = __builtin_amdgcn_readfirstlane(C.tid >> 6);
	.amdhsa_kernel _Z10fwd_kernel4Args
		.amdhsa_group_segment_fixed_size 0
		.amdhsa_private_segment_fixed_size 0
		.amdhsa_kernarg_size 448
		.amdhsa_user_sgpr_count 2
		.amdhsa_user_sgpr_dispatch_ptr 0
		.amdhsa_user_sgpr_queue_ptr 0
		.amdhsa_user_sgpr_kernarg_segment_ptr 1
		.amdhsa_user_sgpr_dispatch_id 0
		.amdhsa_user_sgpr_kernarg_preload_length 0
		.amdhsa_user_sgpr_kernarg_preload_offset 0
		.amdhsa_user_sgpr_private_segment_size 0
		.amdhsa_uses_dynamic_stack 0
		.amdhsa_enable_private_segment 0
		.amdhsa_system_sgpr_workgroup_id_x 1
		.amdhsa_system_sgpr_workgroup_id_y 0
		.amdhsa_system_sgpr_workgroup_id_z 0
		.amdhsa_system_sgpr_workgroup_info 0
		.amdhsa_system_vgpr_workitem_id 2
		.amdhsa_next_free_vgpr 254
		.amdhsa_next_free_sgpr 100
		.amdhsa_accum_offset 256
		.amdhsa_reserve_vcc 1
		.amdhsa_float_round_mode_32 0
		.amdhsa_float_round_mode_16_64 0
		.amdhsa_float_denorm_mode_32 3
		.amdhsa_float_denorm_mode_16_64 3
		.amdhsa_dx10_clamp 1
		.amdhsa_ieee_mode 1
		.amdhsa_fp16_overflow 0
		.amdhsa_tg_split 0
		.amdhsa_exception_fp_ieee_invalid_op 0
		.amdhsa_exception_fp_denorm_src 0
		.amdhsa_exception_fp_ieee_div_zero 0
		.amdhsa_exception_fp_ieee_overflow 0
		.amdhsa_exception_fp_ieee_underflow 0
		.amdhsa_exception_fp_ieee_inexact 0
		.amdhsa_exception_int_div_zero 0
	.end_amdhsa_kernel

; #define LAS __attribute__((address_space(3)))
; __global__ void __launch_bounds__(512, 2) fwd_kernel(Args a) {
;     extern __shared__ __attribute__((aligned(16))) unsigned char lds_raw[];
;     Ctx C;
;     C.lds = (LAS uchar*)lds_raw; C.tid = threadIdx.x; C.lane = C.tid & 63; C.wave = __builtin_amdgcn_readfirstlane(C.tid >> 6);
amdhsa.kernels:
  - .agpr_count:     0
    .args:
      - .offset:         0
        .size:           192
        .value_kind:     by_value
      - .offset:         192
        .size:           4
        .value_kind:     hidden_block_count_x
      - .offset:         196
        .size:           4
        .value_kind:     hidden_block_count_y
      - .offset:         200
        .size:           4
        .value_kind:     hidden_block_count_z
      - .offset:         204
        .size:           2
        .value_kind:     hidden_group_size_x
      - .offset:         206
        .size:           2
        .value_kind:     hidden_group_size_y
      - .offset:         208
        .size:           2
        .value_kind:     hidden_group_size_z
      - .offset:         210
        .size:           2
        .value_kind:     hidden_remainder_x
      - .offset:         212
        .size:           2
        .value_kind:     hidden_remainder_y
      - .offset:         214
        .size:           2
        .value_kind:     hidden_remainder_z
      - .offset:         232
        .size:           8
        .value_kind:     hidden_global_offset_x
      - .offset:         240
        .size:           8
        .value_kind:     hidden_global_offset_y
      - .offset:         248
        .size:           8
        .value_kind:     hidden_global_offset_z
      - .offset:         256
        .size:           2
        .value_kind:     hidden_grid_dims
      - .offset:         280
        .size:           8
        .value_kind:     hidden_multigrid_sync_arg
      - .offset:         312
        .size:           4
        .value_kind:     hidden_dynamic_lds_size
    .group_segment_fixed_size: 0
    .kernarg_segment_align: 8
    .kernarg_segment_size: 448
    .language:       OpenCL C
    .language_version:
      - 2
      - 0
    .max_flat_workgroup_size: 512
    .name:           _Z10fwd_kernel4Args
    .private_segment_fixed_size: 0
    .sgpr_count:     106
    .sgpr_spill_count: 40
    .symbol:         _Z10fwd_kernel4Args.kd
    .uniform_work_group_size: 1
    .uses_dynamic_stack: false
    .vgpr_count:     254
    .vgpr_spill_count: 0
    .wavefront_size: 64
